# v16: v14 plus nt policy on the chain phases' q/k/v tile loads
# baseline (speedup 1.0000x reference)
.LBB0_354:
	s_ashr_i32 s23, s22, 31
	s_lshl_b64 s[0:1], s[22:23], 27
	s_add_u32 s34, s48, s0
	s_addc_u32 s35, s49, s1
	s_cmpk_lt_u32 s69, 0x80
	s_cselect_b64 s[20:21], -1, 0
	s_and_b64 s[0:1], s[20:21], exec
	s_cselect_b32 s0, 0, 0x7c0
	v_cndmask_b32_e64 v2, v161, v160, s[20:21]
	s_or_b32 s38, s72, s0
	v_add_u32_e32 v4, s38, v2
	v_mov_b64_e32 v[2:3], s[30:31]
	v_mad_i64_i32 v[4:5], s[0:1], v4, s57, v[2:3]
	s_lshl_b32 s0, s25, 8
	s_mov_b32 s1, s24
	v_lshl_add_u64 v[4:5], v[4:5], 0, s[0:1]
	v_mov_b32_e32 v153, v151
	v_lshl_add_u64 v[4:5], v[4:5], 0, v[152:153]
	s_waitcnt vmcnt(0)
	flat_load_dwordx4 v[98:101], v[4:5] nt
	flat_load_dwordx4 v[102:105], v[4:5] offset:1024 nt
	v_cndmask_b32_e64 v4, v163, v162, s[20:21]
	v_add_u32_e32 v4, s38, v4
	v_mad_i64_i32 v[4:5], s[22:23], v4, s57, v[2:3]
	v_lshl_add_u64 v[4:5], v[4:5], 0, s[0:1]
	v_lshl_add_u64 v[4:5], v[4:5], 0, v[152:153]
	flat_load_dwordx4 v[106:109], v[4:5] nt
	flat_load_dwordx4 v[110:113], v[4:5] offset:1024 nt
	v_cndmask_b32_e64 v4, v165, v164, s[20:21]
	v_add_u32_e32 v4, s38, v4
	v_cndmask_b32_e64 v6, v167, v166, s[20:21]
	v_mad_i64_i32 v[4:5], s[22:23], v4, s57, v[2:3]
	s_lshl_b32 s36, s25, 9
	s_mov_b32 s37, s24
	v_add_u32_e32 v6, s38, v6
	v_lshl_add_u64 v[4:5], v[4:5], 0, s[36:37]
	v_mov_b32_e32 v155, v151
	v_mad_i64_i32 v[6:7], s[22:23], v6, s57, v[2:3]
	v_lshl_add_u64 v[4:5], v[4:5], 0, v[154:155]
	v_lshl_add_u64 v[6:7], v[6:7], 0, s[36:37]
	v_lshl_add_u64 v[6:7], v[6:7], 0, v[154:155]
	flat_load_dwordx4 v[114:117], v[4:5] offset:2048 nt
	flat_load_dwordx4 v[118:121], v[6:7] offset:2048 nt
	v_cndmask_b32_e64 v4, v169, v168, s[20:21]
	v_add_u32_e32 v4, s38, v4
	v_cndmask_b32_e64 v6, v171, v170, s[20:21]
	v_mad_i64_i32 v[4:5], s[22:23], v4, s57, v[2:3]
	v_add_u32_e32 v6, s38, v6
	v_lshl_add_u64 v[4:5], v[4:5], 0, s[36:37]
	v_mad_i64_i32 v[2:3], s[22:23], v6, s57, v[2:3]
	v_lshl_add_u64 v[4:5], v[4:5], 0, v[154:155]
	v_lshl_add_u64 v[2:3], v[2:3], 0, s[36:37]
	v_lshl_add_u64 v[2:3], v[2:3], 0, v[154:155]
	flat_load_dwordx4 v[122:125], v[4:5] offset:2048 nt
	flat_load_dwordx4 v[126:129], v[2:3] offset:2048 nt
	s_add_u32 s1, s34, s36
	s_addc_u32 s23, s35, 0
	s_add_u32 s22, s1, s58
	s_addc_u32 s23, s23, 0
	s_add_u32 s34, s30, s0
	s_addc_u32 s35, s31, 0
	s_add_u32 s36, s30, s36
	s_mov_b32 s73, 0
	s_addc_u32 s37, s31, 0
	s_mov_b32 s76, 30
	v_mov_b32_e32 v155, 0
	v_mov_b32_e32 v2, 0
	v_mov_b32_e32 v3, 0
	v_mov_b32_e32 v4, 0
	v_mov_b32_e32 v5, 0
	v_mov_b32_e32 v6, 0
	v_mov_b32_e32 v7, 0
	v_mov_b32_e32 v8, 0
	v_mov_b32_e32 v9, 0
	v_mov_b32_e32 v10, 0
	v_mov_b32_e32 v11, 0
	v_mov_b32_e32 v12, 0
	v_mov_b32_e32 v13, 0
	v_mov_b32_e32 v14, 0
	v_mov_b32_e32 v15, 0
	v_mov_b32_e32 v16, 0
	v_mov_b32_e32 v17, 0
	v_mov_b32_e32 v18, 0
	v_mov_b32_e32 v19, 0
	v_mov_b32_e32 v20, 0
	v_mov_b32_e32 v21, 0
	v_mov_b32_e32 v22, 0
	v_mov_b32_e32 v23, 0
	v_mov_b32_e32 v24, 0
	v_mov_b32_e32 v25, 0
	v_mov_b32_e32 v26, 0
	v_mov_b32_e32 v27, 0
	v_mov_b32_e32 v28, 0
	v_mov_b32_e32 v29, 0
	v_mov_b32_e32 v30, 0
	v_mov_b32_e32 v31, 0
	v_mov_b32_e32 v32, 0
	v_mov_b32_e32 v33, 0
	v_mov_b32_e32 v34, 0
	v_mov_b32_e32 v35, 0
	v_mov_b32_e32 v36, 0
	v_mov_b32_e32 v37, 0
	v_mov_b32_e32 v38, 0
	v_mov_b32_e32 v39, 0
	v_mov_b32_e32 v40, 0
	v_mov_b32_e32 v41, 0
	v_mov_b32_e32 v42, 0
	v_mov_b32_e32 v43, 0
	v_mov_b32_e32 v44, 0
	v_mov_b32_e32 v45, 0
	v_mov_b32_e32 v46, 0
	v_mov_b32_e32 v47, 0
	v_mov_b32_e32 v48, 0
	v_mov_b32_e32 v49, 0
	v_mov_b32_e32 v50, 0
	v_mov_b32_e32 v51, 0
	v_mov_b32_e32 v52, 0
	v_mov_b32_e32 v53, 0
	v_mov_b32_e32 v54, 0
	v_mov_b32_e32 v55, 0
	v_mov_b32_e32 v56, 0
	v_mov_b32_e32 v57, 0
	v_mov_b32_e32 v58, 0
	v_mov_b32_e32 v59, 0
	v_mov_b32_e32 v60, 0
	v_mov_b32_e32 v61, 0
	v_mov_b32_e32 v62, 0
	v_mov_b32_e32 v63, 0
	v_mov_b32_e32 v64, 0
	v_mov_b32_e32 v65, 0
	s_mov_b32 s77, 0
	s_mov_b32 s80, 0
	s_waitcnt lgkmcnt(0)
	s_barrier
	s_branch .LBB0_356

.LBB0_356:
	s_add_i32 s79, s77, 0
	s_add_i32 s0, s79, 0x1c0fc
	v_mov_b32_e32 v72, v156
	v_mov_b32_e32 v66, s0
	ds_read_b32 v67, v66
	v_and_b32_e32 v66, 15, v72
	v_lshlrev_b32_e32 v73, 4, v66
	v_ashrrev_i32_e32 v66, 4, v72
	v_and_b32_e32 v74, 0x70, v72
	v_lshlrev_b32_e32 v68, 8, v66
	v_bitop3_b32 v68, v73, v68, v74 bitop3:0xde
	v_add_u32_e32 v68, 0, v68
	s_waitcnt vmcnt(0)
	ds_write_b128 v68, v[98:101]
	ds_write_b128 v68, v[102:105] offset:16384
	v_lshl_add_u32 v68, v66, 2, s79
	v_add_u32_e32 v68, 0x1a000, v68
	ds_read_b32 v68, v68
	s_waitcnt lgkmcnt(0)
	v_max_f32_e32 v67, v67, v67
	v_max_f32_e32 v185, v155, v155
	v_max_f32_e32 v153, v185, v67
	v_and_b32_e32 v69, 0xffff0000, v102
	s_waitcnt lgkmcnt(0)
	v_sub_f32_e32 v67, v68, v153
	v_mul_f32_e32 v67, 0x3fb8aa3b, v67
	v_exp_f32_e32 v67, v67
	v_lshlrev_b32_e32 v68, 16, v102
	v_and_b32_e32 v70, 0xffff0000, v103
	v_and_b32_e32 v71, 0xffff0000, v104
	v_mul_f32_e32 v68, v67, v68
	v_mul_f32_e32 v69, v67, v69
	v_cvt_pk_bf16_f32 v68, v68, v69
	v_lshlrev_b32_e32 v69, 16, v103
	v_mul_f32_e32 v69, v67, v69
	v_mul_f32_e32 v70, v67, v70
	v_cvt_pk_bf16_f32 v69, v69, v70
	v_lshlrev_b32_e32 v70, 16, v104
	v_mul_f32_e32 v70, v67, v70
	v_mul_f32_e32 v71, v67, v71
	v_cvt_pk_bf16_f32 v70, v70, v71
	v_lshlrev_b32_e32 v71, 16, v105
	v_and_b32_e32 v77, 0xffff0000, v105
	v_mul_f32_e32 v71, v67, v71
	v_mul_f32_e32 v67, v67, v77
	v_cvt_pk_bf16_f32 v71, v71, v67
	v_and_b32_e32 v67, 0xfffff0, v66
	v_lshlrev_b32_e32 v77, 1, v66
	v_and_or_b32 v67, v77, 8, v67
	v_bfe_u32 v75, v72, 2, 2
	v_lshrrev_b32_e32 v77, 1, v66
	v_lshrrev_b32_e32 v67, 1, v67
	v_and_b32_e32 v78, 3, v66
	v_or_b32_e32 v67, v67, v75
	v_and_or_b32 v77, v77, 4, v78
	v_and_b32_e32 v76, 48, v73
	v_lshlrev_b32_e32 v77, 6, v77
	v_lshl_add_u32 v67, v67, 9, 0
	v_add3_u32 v67, v67, v77, v76
	v_add_u32_e32 v77, 0x200, v72
	ds_write_b128 v67, v[68:71] offset:32768
	v_ashrrev_i32_e32 v67, 4, v77
	v_lshlrev_b32_e32 v68, 8, v67
	v_bitop3_b32 v68, v68, v73, v74 bitop3:0xf6
	v_add_u32_e32 v68, 0, v68
	ds_write_b128 v68, v[106:109]
	ds_write_b128 v68, v[110:113] offset:16384
	v_lshl_add_u32 v68, v67, 2, s79
	v_add_u32_e32 v68, 0x1a000, v68
	ds_read_b32 v68, v68
	v_and_b32_e32 v69, 0xffff0000, v110
	v_and_b32_e32 v70, 0xffff0000, v111
	v_and_b32_e32 v73, 0xffff0000, v112
	v_and_b32_e32 v74, 0xffff0000, v113
	s_waitcnt lgkmcnt(0)
	v_sub_f32_e32 v68, v68, v153
	v_mul_f32_e32 v68, 0x3fb8aa3b, v68
	v_exp_f32_e32 v71, v68
	v_lshlrev_b32_e32 v68, 16, v110
	s_add_i32 s78, s80, 1
	s_cmpk_eq_i32 s77, 0x1f00
	v_mul_f32_e32 v68, v71, v68
	v_mul_f32_e32 v69, v71, v69
	v_cvt_pk_bf16_f32 v68, v68, v69
	v_lshlrev_b32_e32 v69, 16, v111
	v_mul_f32_e32 v69, v71, v69
	v_mul_f32_e32 v70, v71, v70
	v_cvt_pk_bf16_f32 v69, v69, v70
	v_lshlrev_b32_e32 v70, 16, v112
	v_mul_f32_e32 v70, v71, v70
	v_mul_f32_e32 v73, v71, v73
	v_cvt_pk_bf16_f32 v70, v70, v73
	v_lshlrev_b32_e32 v73, 16, v113
	v_mul_f32_e32 v73, v71, v73
	v_mul_f32_e32 v71, v71, v74
	v_cvt_pk_bf16_f32 v71, v73, v71
	v_and_b32_e32 v73, 0xfffff0, v67
	v_lshlrev_b32_e32 v74, 1, v67
	v_and_or_b32 v73, v74, 8, v73
	v_lshrrev_b32_e32 v73, 1, v73
	v_lshrrev_b32_e32 v74, 1, v67
	v_or_b32_e32 v73, v73, v75
	v_and_b32_e32 v75, 3, v67
	v_and_or_b32 v74, v74, 4, v75
	v_lshlrev_b32_e32 v74, 6, v74
	v_lshl_add_u32 v73, v73, 9, 0
	v_add3_u32 v73, v73, v74, v76
	ds_write_b128 v73, v[68:71] offset:32768
	v_lshlrev_b32_e32 v69, 4, v72
	v_lshlrev_b32_e32 v68, 10, v72
	v_and_b32_e32 v75, 48, v69
	v_ashrrev_i32_e32 v69, 5, v72
	v_and_b32_e32 v68, 0x4000, v68
	v_and_b32_e32 v70, 0xfffff0, v69
	v_lshlrev_b32_e32 v71, 1, v69
	v_add_u32_e32 v73, 0, v68
	v_lshlrev_b32_e32 v68, 3, v72
	v_and_or_b32 v70, v71, 8, v70
	v_bfe_u32 v74, v68, 5, 2
	v_lshrrev_b32_e32 v71, 1, v69
	v_lshrrev_b32_e32 v70, 1, v70
	v_and_b32_e32 v76, 3, v69
	v_or_b32_e32 v70, v70, v74
	v_and_or_b32 v71, v71, 4, v76
	v_lshlrev_b32_e32 v71, 6, v71
	v_lshl_add_u32 v70, v70, 9, v73
	v_add3_u32 v70, v70, v71, v75
	ds_write_b128 v70, v[114:117] offset:49152
	v_ashrrev_i32_e32 v70, 5, v77
	v_and_b32_e32 v71, 0xfffff0, v70
	v_lshlrev_b32_e32 v76, 1, v70
	v_and_or_b32 v71, v76, 8, v71
	v_lshrrev_b32_e32 v76, 1, v70
	v_lshrrev_b32_e32 v71, 1, v71
	v_and_b32_e32 v77, 3, v70
	v_or_b32_e32 v71, v71, v74
	v_and_or_b32 v76, v76, 4, v77
	v_lshlrev_b32_e32 v76, 6, v76
	v_lshl_add_u32 v71, v71, 9, v73
	v_add3_u32 v71, v71, v76, v75
	ds_write_b128 v71, v[118:121] offset:49152
	v_add_u32_e32 v71, 0x400, v72
	v_ashrrev_i32_e32 v71, 5, v71
	v_and_b32_e32 v76, 0xfffff0, v71
	v_lshlrev_b32_e32 v77, 1, v71
	v_and_or_b32 v76, v77, 8, v76
	v_lshrrev_b32_e32 v77, 1, v71
	v_lshrrev_b32_e32 v76, 1, v76
	v_and_b32_e32 v78, 3, v71
	v_or_b32_e32 v76, v76, v74
	v_and_or_b32 v77, v77, 4, v78
	v_lshlrev_b32_e32 v77, 6, v77
	v_lshl_add_u32 v76, v76, 9, v73
	v_add_u32_e32 v72, 0x600, v72
	v_add3_u32 v76, v76, v77, v75
	v_ashrrev_i32_e32 v72, 5, v72
	ds_write_b128 v76, v[122:125] offset:49152
	v_and_b32_e32 v76, 0xfffff0, v72
	v_lshlrev_b32_e32 v77, 1, v72
	v_and_or_b32 v76, v77, 8, v76
	v_lshrrev_b32_e32 v76, 1, v76
	v_lshrrev_b32_e32 v77, 1, v72
	v_or_b32_e32 v74, v76, v74
	v_and_b32_e32 v76, 3, v72
	v_and_or_b32 v76, v77, 4, v76
	v_lshlrev_b32_e32 v76, 6, v76
	v_lshl_add_u32 v73, v74, 9, v73
	v_add3_u32 v73, v73, v76, v75
	ds_write_b128 v73, v[126:129] offset:49152
	s_cbranch_scc1 .LBB0_358
	s_and_b64 s[0:1], s[20:21], exec
	s_cselect_b32 s0, s78, s76
	s_lshl_b32 s0, s0, 6
	v_sub_u32_e32 v74, 63, v66
	v_cndmask_b32_e64 v66, v74, v66, s[20:21]
	s_add_i32 s25, s0, s72
	v_add_u32_e32 v66, s25, v66
	v_mov_b64_e32 v[74:75], s[34:35]
	v_mad_i64_i32 v[76:77], s[0:1], v66, s57, v[74:75]
	v_sub_u32_e32 v66, 63, v67
	v_cndmask_b32_e64 v66, v66, v67, s[20:21]
	v_and_b32_e32 v73, 0x78, v68
	v_add_u32_e32 v66, s25, v66
	v_lshlrev_b32_e32 v150, 1, v73
	v_mad_i64_i32 v[66:67], s[0:1], v66, s57, v[74:75]
	v_lshl_add_u64 v[76:77], v[76:77], 0, v[150:151]
	v_lshl_add_u64 v[66:67], v[66:67], 0, v[150:151]
	flat_load_dwordx4 v[98:101], v[76:77] nt
	flat_load_dwordx4 v[102:105], v[76:77] offset:1024 nt
	flat_load_dwordx4 v[106:109], v[66:67] nt
	flat_load_dwordx4 v[110:113], v[66:67] offset:1024 nt
	v_sub_u32_e32 v66, 63, v69
	v_cndmask_b32_e64 v66, v66, v69, s[20:21]
	v_sub_u32_e32 v73, 63, v70
	v_add_u32_e32 v69, s25, v66
	v_mov_b64_e32 v[66:67], s[36:37]
	v_and_b32_e32 v68, 0xf8, v68
	v_cndmask_b32_e64 v70, v73, v70, s[20:21]
	v_mad_i64_i32 v[74:75], s[0:1], v69, s57, v[66:67]
	v_lshlrev_b32_e32 v150, 1, v68
	v_add_u32_e32 v70, s25, v70
	v_lshl_add_u64 v[68:69], v[74:75], 0, v[150:151]
	v_mad_i64_i32 v[74:75], s[0:1], v70, s57, v[66:67]
	v_lshl_add_u64 v[74:75], v[74:75], 0, v[150:151]
	flat_load_dwordx4 v[114:117], v[68:69] offset:2048 nt
	flat_load_dwordx4 v[118:121], v[74:75] offset:2048 nt
	v_sub_u32_e32 v68, 63, v71
	v_cndmask_b32_e64 v68, v68, v71, s[20:21]
	v_sub_u32_e32 v70, 63, v72
	v_add_u32_e32 v68, s25, v68
	v_cndmask_b32_e64 v70, v70, v72, s[20:21]
	v_mad_i64_i32 v[68:69], s[0:1], v68, s57, v[66:67]
	v_add_u32_e32 v70, s25, v70
	v_lshl_add_u64 v[68:69], v[68:69], 0, v[150:151]
	v_mad_i64_i32 v[66:67], s[0:1], v70, s57, v[66:67]
	v_lshl_add_u64 v[66:67], v[66:67], 0, v[150:151]
	flat_load_dwordx4 v[122:125], v[68:69] offset:2048 nt
	flat_load_dwordx4 v[126:129], v[66:67] offset:2048 nt

.LBB0_961:
	s_ashr_i32 s14, s46, 7
	s_and_b32 s28, s46, 3
	s_ashr_i32 s15, s14, 31
	s_lshl_b32 s0, s28, 7
	s_lshl_b64 s[12:13], s[14:15], 15
	v_or_b32_e32 v14, s0, v171
	s_waitcnt lgkmcnt(0)
	s_add_u32 s12, s16, s12
	s_addc_u32 s13, s17, s13
	v_lshlrev_b32_e32 v84, 2, v14
	v_lshl_add_u64 v[2:3], s[12:13], 0, v[84:85]
	v_lshl_add_u64 v[2:3], v[2:3], 0, v[156:157]
	s_movk_i32 s1, 0x1000
	v_add_co_u32_e32 v10, vcc, s1, v2
	s_movk_i32 s1, 0x2000
	s_nop 0
	v_addc_co_u32_e32 v11, vcc, 0, v3, vcc
	v_add_co_u32_e32 v6, vcc, s1, v2
	s_movk_i32 s1, 0x3000
	s_nop 0
	v_addc_co_u32_e32 v7, vcc, 0, v3, vcc
	v_add_co_u32_e32 v12, vcc, s1, v2
	s_cmpk_lt_u32 s46, 0x80
	global_load_dword v4, v[6:7], off offset:-4096
	global_load_dword v5, v[6:7], off
	s_nop 0
	global_load_dword v6, v[6:7], off offset:2048
	v_addc_co_u32_e32 v13, vcc, 0, v3, vcc
	global_load_dword v7, v[2:3], off
	global_load_dword v8, v[2:3], off offset:2048
	global_load_dword v9, v[10:11], off offset:2048
	s_nop 0
	global_load_dword v10, v[12:13], off
	global_load_dword v11, v[12:13], off offset:2048
	v_lshl_or_b32 v2, s14, 9, v14
	s_cselect_b64 s[12:13], -1, 0
	v_ashrrev_i32_e32 v3, 31, v2
	s_and_b64 s[26:27], s[12:13], exec
	v_lshl_add_u64 v[2:3], v[2:3], 2, s[18:19]
	s_cselect_b32 s1, 0, 0x7e0
	s_lshl_b32 s20, s46, 9
	global_load_dword v180, v[2:3], off
	v_cndmask_b32_e64 v2, v173, v172, s[12:13]
	s_and_b32 s47, s20, 0xf800
	v_add_u32_e32 v15, s47, v2
	v_add_u32_e32 v2, s1, v15
	v_mad_i64_i32 v[2:3], s[26:27], v2, s39, v[160:161]
	s_lshl_b32 s20, s28, 8
	v_lshl_add_u64 v[2:3], v[2:3], 0, s[20:21]
	v_lshl_add_u64 v[2:3], v[2:3], 0, v[164:165]
	s_waitcnt vmcnt(0)
	flat_load_dwordx4 v[88:91], v[2:3] nt
	flat_load_dwordx4 v[92:95], v[2:3] offset:1024 nt
	v_cndmask_b32_e64 v2, v175, v174, s[12:13]
	v_add_u32_e32 v13, s47, v2
	v_add_u32_e32 v2, s1, v13
	v_cndmask_b32_e64 v12, v177, v176, s[12:13]
	v_mad_i64_i32 v[2:3], s[26:27], v2, s39, v[160:161]
	v_add_u32_e32 v14, s47, v12
	s_lshl_b32 s26, s28, 9
	s_mov_b32 s27, s21
	v_add_u32_e32 v12, s1, v14
	v_lshl_add_u64 v[2:3], v[2:3], 0, s[26:27]
	v_mad_i64_i32 v[16:17], s[28:29], v12, s39, v[160:161]
	v_lshl_add_u64 v[2:3], v[2:3], 0, v[168:169]
	v_lshl_add_u64 v[16:17], v[16:17], 0, s[26:27]
	v_lshl_add_u64 v[16:17], v[16:17], 0, v[168:169]
	flat_load_dwordx4 v[96:99], v[2:3] offset:2048 nt
	flat_load_dwordx4 v[100:103], v[16:17] offset:2048 nt
	v_mov_b32_e32 v86, v85
	v_mov_b32_e32 v87, v85
	v_mov_b32_e32 v84, v85
	v_cndmask_b32_e64 v2, v178, v170, s[12:13]
	v_mov_b64_e32 v[106:107], v[86:87]
	v_mov_b64_e32 v[110:111], v[86:87]
	s_and_b64 vcc, exec, s[8:9]
	v_or_b32_e32 v12, s47, v2
	v_lshlrev_b32_e32 v2, 2, v158
	v_mov_b64_e32 v[104:105], v[84:85]
	v_mov_b64_e32 v[108:109], v[84:85]
	s_cbranch_vccnz .LBB0_963
	v_or_b32_e32 v3, s1, v12
	v_lshlrev_b32_e32 v84, 7, v3
	s_lshl_b32 s26, s14, 4
	v_lshl_add_u64 v[16:17], s[24:25], 0, v[84:85]
	s_ashr_i32 s27, s26, 31
	v_lshl_add_u64 v[16:17], s[26:27], 2, v[16:17]
	v_mov_b32_e32 v3, v85
	v_lshl_add_u64 v[16:17], v[16:17], 0, v[2:3]
	flat_load_dwordx4 v[104:107], v[16:17] nt
	flat_load_dwordx4 v[108:111], v[16:17] offset:16 nt
.LBB0_963:
	s_and_b64 s[26:27], s[12:13], exec
	s_cselect_b32 s1, 32, 0x7c0
	v_add_u32_e32 v3, s1, v15
	v_mov_b64_e32 v[16:17], s[22:23]
	v_mad_i64_i32 v[18:19], s[26:27], v3, s39, v[16:17]
	s_lshl_b32 s30, s0, 1
	s_mov_b32 s31, s21
	v_lshl_add_u64 v[18:19], v[18:19], 0, s[30:31]
	v_mov_b32_e32 v163, v85
	v_lshl_add_u64 v[18:19], v[18:19], 0, v[162:163]
	v_add_u32_e32 v3, s1, v13
	flat_load_dwordx4 v[112:115], v[18:19] nt
	flat_load_dwordx4 v[116:119], v[18:19] offset:1024 nt
	v_mad_i64_i32 v[18:19], s[26:27], v3, s39, v[16:17]
	s_lshl_b32 s20, s20, 1
	v_add_u32_e32 v3, s1, v14
	v_lshl_add_u64 v[18:19], v[18:19], 0, s[20:21]
	v_mov_b32_e32 v167, v85
	v_mad_i64_i32 v[14:15], s[26:27], v3, s39, v[16:17]
	v_lshl_add_u64 v[18:19], v[18:19], 0, v[166:167]
	v_lshl_add_u64 v[14:15], v[14:15], 0, s[20:21]
	v_lshl_add_u64 v[14:15], v[14:15], 0, v[166:167]
	flat_load_dwordx4 v[120:123], v[18:19] offset:2048 nt
	flat_load_dwordx4 v[124:127], v[14:15] offset:2048 nt
	s_andn2_b64 vcc, exec, s[64:65]
	s_mov_b64 s[28:29], -1
	s_cbranch_vccnz .LBB0_965
	s_lshl_b32 s26, s14, 4
	s_ashr_i32 s27, s26, 31
	s_mov_b64 s[28:29], 0
.LBB0_965:
	s_andn2_b64 vcc, exec, s[28:29]
	s_cbranch_vccnz .LBB0_967
	v_or_b32_e32 v3, s1, v12
	v_lshlrev_b32_e32 v84, 7, v3
	s_lshl_b32 s26, s14, 4
	v_lshl_add_u64 v[12:13], s[24:25], 0, v[84:85]
	s_ashr_i32 s27, s26, 31
	v_lshl_add_u64 v[12:13], s[26:27], 2, v[12:13]
	v_mov_b32_e32 v3, v85
	v_lshl_add_u64 v[2:3], v[12:13], 0, v[2:3]
	flat_load_dwordx4 v[132:135], v[2:3] nt
	flat_load_dwordx4 v[136:139], v[2:3] offset:16 nt
	s_branch .LBB0_968

.LBB0_974:
	v_mov_b32_e32 v66, v159
	s_waitcnt lgkmcnt(0)
	s_barrier
	s_add_i32 s50, 0, 0x10000
	v_ashrrev_i32_e32 v67, 5, v66
	v_lshlrev_b32_e32 v68, 10, v66
	v_and_b32_e32 v70, 0xfffff0, v67
	v_lshlrev_b32_e32 v71, 1, v67
	v_and_b32_e32 v69, 0x4000, v68
	v_lshlrev_b32_e32 v68, 3, v66
	v_and_or_b32 v70, v71, 8, v70
	v_lshrrev_b32_e32 v71, 1, v67
	v_and_b32_e32 v73, 3, v67
	v_lshrrev_b32_e32 v70, 1, v70
	v_bfe_u32 v72, v68, 5, 2
	v_and_or_b32 v71, v71, 4, v73
	v_or_b32_e32 v70, v70, v72
	v_lshlrev_b32_e32 v71, 6, v71
	v_lshlrev_b32_e32 v73, 4, v66
	v_lshlrev_b32_e32 v70, 9, v70
	v_and_b32_e32 v73, 48, v73
	v_add3_u32 v71, 0, v69, v71
	v_add3_u32 v69, v71, v70, v73
	s_waitcnt vmcnt(0)
	ds_write_b128 v69, v[96:99] offset:32768
	v_add_u32_e32 v69, 16, v67
	v_and_b32_e32 v70, 0xfffff0, v69
	v_lshlrev_b32_e32 v74, 1, v69
	v_and_or_b32 v70, v74, 8, v70
	v_lshrrev_b32_e32 v70, 1, v70
	v_or_b32_e32 v70, v70, v72
	v_lshlrev_b32_e32 v70, 9, v70
	v_add3_u32 v70, v71, v70, v73
	ds_write_b128 v70, v[100:103] offset:32768
	v_ashrrev_i32_e32 v70, 4, v66
	v_and_b32_e32 v71, 15, v66
	v_lshlrev_b32_e32 v72, 9, v70
	v_lshlrev_b32_e32 v73, 5, v71
	v_add3_u32 v76, s50, v72, v73
	v_add_u32_e32 v72, 0, v73
	v_add_u32_e32 v84, 0x14000, v72
	ds_read_b128 v[72:75], v76
	ds_read_b128 v[76:79], v76 offset:16
	ds_read_b128 v[80:83], v84
	ds_read_b128 v[140:143], v84 offset:16
	v_lshlrev_b32_e32 v84, 16, v88
	s_waitcnt lgkmcnt(3)
	v_mul_f32_e32 v72, 0x3fb8aa3b, v72
	v_exp_f32_e32 v72, v72
	v_mul_f32_e32 v73, 0x3fb8aa3b, v73
	v_mul_f32_e32 v74, 0x3fb8aa3b, v74
	v_mul_f32_e32 v75, 0x3fb8aa3b, v75
	s_waitcnt lgkmcnt(2)
	v_mul_f32_e32 v76, 0x3fb8aa3b, v76
	v_mul_f32_e32 v77, 0x3fb8aa3b, v77
	v_exp_f32_e32 v73, v73
	v_exp_f32_e32 v74, v74
	v_exp_f32_e32 v75, v75
	v_exp_f32_e32 v76, v76
	v_exp_f32_e32 v77, v77
	v_mul_f32_e32 v78, 0x3fb8aa3b, v78
	v_mul_f32_e32 v79, 0x3fb8aa3b, v79
	v_exp_f32_e32 v78, v78
	v_exp_f32_e32 v79, v79
	v_and_b32_e32 v144, 0xffff0000, v88
	v_lshlrev_b32_e32 v145, 16, v89
	v_and_b32_e32 v146, 0xffff0000, v89
	v_lshlrev_b32_e32 v147, 16, v90
	v_and_b32_e32 v148, 0xffff0000, v90
	v_rcp_f32_e32 v86, v72
	v_mul_f32_e32 v72, v72, v84
	s_waitcnt lgkmcnt(0)
	v_mul_f32_e32 v84, 0x3fb8aa3b, v140
	v_rcp_f32_e32 v87, v73
	v_mul_f32_e32 v73, v73, v144
	v_rcp_f32_e32 v144, v74
	v_mul_f32_e32 v74, v74, v145
	v_rcp_f32_e32 v145, v75
	v_mul_f32_e32 v75, v75, v146
	v_rcp_f32_e32 v146, v76
	v_mul_f32_e32 v76, v76, v147
	v_exp_f32_e32 v140, v84
	v_rcp_f32_e32 v147, v77
	v_mul_f32_e32 v77, v77, v148
	v_mul_f32_e32 v84, 0x3fb8aa3b, v141
	v_lshlrev_b32_e32 v149, 16, v91
	v_and_b32_e32 v150, 0xffff0000, v91
	v_mul_f32_e32 v80, 0x3fb8aa3b, v80
	v_mul_f32_e32 v81, 0x3fb8aa3b, v81
	v_exp_f32_e32 v141, v84
	v_mul_f32_e32 v84, 0x3fb8aa3b, v142
	v_cvt_pk_bf16_f32 v72, v72, v73
	v_cvt_pk_bf16_f32 v73, v74, v75
	v_cvt_pk_bf16_f32 v74, v76, v77
	v_lshlrev_b32_e32 v76, 8, v70
	v_lshlrev_b32_e32 v71, 4, v71
	v_and_b32_e32 v77, 0x70, v66
	v_exp_f32_e32 v80, v80
	v_exp_f32_e32 v81, v81
	v_rcp_f32_e32 v148, v78
	v_mul_f32_e32 v78, v78, v149
	v_exp_f32_e32 v142, v84
	v_rcp_f32_e32 v149, v79
	v_mul_f32_e32 v79, v79, v150
	v_mul_f32_e32 v84, 0x3fb8aa3b, v143
	v_bitop3_b32 v76, v71, v76, v77 bitop3:0xde
	v_exp_f32_e32 v143, v84
	v_cvt_pk_bf16_f32 v75, v78, v79
	v_add_u32_e32 v84, 0, v76
	v_mul_f32_e32 v82, 0x3fb8aa3b, v82
	v_mul_f32_e32 v83, 0x3fb8aa3b, v83
	ds_write_b128 v84, v[72:75]
	v_lshlrev_b32_e32 v72, 16, v92
	v_and_b32_e32 v73, 0xffff0000, v92
	v_exp_f32_e32 v82, v82
	v_exp_f32_e32 v83, v83
	v_pk_mul_f32 v[72:73], v[86:87], v[72:73]
	s_add_i32 s49, s20, -3
	v_pk_mul_f32 v[74:75], v[72:73], v[80:81]
	v_cvt_pk_bf16_f32 v72, v72, v73
	v_cvt_pk_bf16_f32 v76, v74, v75
	v_lshlrev_b32_e32 v74, 16, v93
	v_and_b32_e32 v75, 0xffff0000, v93
	v_pk_mul_f32 v[74:75], v[144:145], v[74:75]
	v_lshlrev_b32_e32 v80, 16, v95
	v_pk_mul_f32 v[78:79], v[74:75], v[82:83]
	v_cvt_pk_bf16_f32 v73, v74, v75
	v_lshlrev_b32_e32 v74, 16, v94
	v_and_b32_e32 v75, 0xffff0000, v94
	v_and_b32_e32 v81, 0xffff0000, v95
	v_pk_mul_f32 v[74:75], v[146:147], v[74:75]
	v_pk_mul_f32 v[80:81], v[148:149], v[80:81]
	v_cvt_pk_bf16_f32 v77, v78, v79
	v_pk_mul_f32 v[78:79], v[74:75], v[140:141]
	v_cvt_pk_bf16_f32 v74, v74, v75
	v_cvt_pk_bf16_f32 v75, v80, v81
	ds_write_b128 v84, v[72:75] offset:8192
	v_and_b32_e32 v72, 0xfffff0, v70
	v_lshlrev_b32_e32 v73, 1, v70
	v_and_or_b32 v72, v73, 8, v72
	v_lshrrev_b32_e32 v72, 1, v72
	v_bfe_u32 v74, v66, 2, 2
	v_lshrrev_b32_e32 v73, 1, v70
	v_or_b32_e32 v72, v72, v74
	v_and_b32_e32 v74, 3, v70
	v_and_or_b32 v73, v73, 4, v74
	v_pk_mul_f32 v[82:83], v[80:81], v[142:143]
	v_lshlrev_b32_e32 v73, 6, v73
	v_and_b32_e32 v71, 48, v71
	v_lshl_add_u32 v72, v72, 9, 0
	s_cmp_lt_u32 s49, 62
	v_cvt_pk_bf16_f32 v78, v78, v79
	v_cvt_pk_bf16_f32 v79, v82, v83
	v_add3_u32 v71, v72, v73, v71
	s_cselect_b64 s[36:37], -1, 0
	s_cmp_gt_u32 s49, 61
	ds_write_b128 v71, v[76:79] offset:16384
	s_cbranch_scc1 .LBB0_977
	s_add_i32 s14, s20, -1
	s_add_i32 s15, s48, -2
	s_and_b64 s[0:1], s[12:13], exec
	s_cselect_b32 s0, s14, s15
	s_lshl_b32 s0, s0, 5
	v_sub_u32_e32 v71, 31, v70
	v_cndmask_b32_e64 v70, v71, v70, s[12:13]
	s_add_i32 s0, s0, s47
	v_and_b32_e32 v72, 0x78, v68
	v_add_u32_e32 v73, s0, v70
	v_mov_b64_e32 v[70:71], s[30:31]
	v_mad_i64_i32 v[70:71], s[14:15], v73, s39, v[70:71]
	v_lshlrev_b32_e32 v84, 1, v72
	v_lshl_add_u64 v[70:71], v[70:71], 0, v[84:85]
	flat_load_dwordx4 v[88:91], v[70:71] nt
	flat_load_dwordx4 v[92:95], v[70:71] offset:1024 nt
	v_sub_u32_e32 v70, 31, v67
	v_cndmask_b32_e64 v70, v70, v67, s[12:13]
	v_sub_u32_e32 v67, 15, v67
	v_add_u32_e32 v72, s0, v70
	v_mov_b64_e32 v[70:71], s[34:35]
	v_and_b32_e32 v68, 0xf8, v68
	v_cndmask_b32_e64 v67, v67, v69, s[12:13]
	v_mad_i64_i32 v[72:73], s[14:15], v72, s39, v[70:71]
	v_lshlrev_b32_e32 v84, 1, v68
	v_add_u32_e32 v67, s0, v67
	v_lshl_add_u64 v[72:73], v[72:73], 0, v[84:85]
	v_mad_i64_i32 v[68:69], s[14:15], v67, s39, v[70:71]
	v_lshl_add_u64 v[68:69], v[68:69], 0, v[84:85]
	flat_load_dwordx4 v[96:99], v[72:73] offset:2048 nt
	flat_load_dwordx4 v[100:103], v[68:69] offset:2048 nt
	s_and_b64 vcc, exec, s[8:9]
	s_cbranch_vccnz .LBB0_977
	v_and_b32_e32 v67, 31, v66
	v_bitop3_b32 v68, v66, 31, v66 bitop3:0xc
	v_cndmask_b32_e64 v67, v68, v67, s[12:13]
	v_or_b32_e32 v67, s0, v67
	v_lshlrev_b32_e32 v84, 7, v67
	v_lshl_add_u64 v[68:69], s[26:27], 0, v[84:85]
	v_and_b32_e32 v84, 32, v66
	v_lshl_add_u64 v[66:67], v[68:69], 0, v[84:85]
	flat_load_dwordx4 v[104:107], v[66:67] nt
	flat_load_dwordx4 v[108:111], v[66:67] offset:16 nt

.LBB0_981:
	v_mov_b32_e32 v66, v159
	s_waitcnt lgkmcnt(0)
	s_barrier
	v_and_b32_e32 v144, 0xffff0000, v112
	v_ashrrev_i32_e32 v67, 5, v66
	v_lshlrev_b32_e32 v68, 10, v66
	v_and_b32_e32 v70, 0xfffff0, v67
	v_lshlrev_b32_e32 v71, 1, v67
	v_and_b32_e32 v69, 0x4000, v68
	v_lshlrev_b32_e32 v68, 3, v66
	v_and_or_b32 v70, v71, 8, v70
	v_lshrrev_b32_e32 v71, 1, v67
	v_and_b32_e32 v73, 3, v67
	v_lshrrev_b32_e32 v70, 1, v70
	v_bfe_u32 v72, v68, 5, 2
	v_and_or_b32 v71, v71, 4, v73
	v_or_b32_e32 v70, v70, v72
	v_lshlrev_b32_e32 v71, 6, v71
	v_lshlrev_b32_e32 v73, 4, v66
	v_lshlrev_b32_e32 v70, 9, v70
	v_and_b32_e32 v73, 48, v73
	v_add3_u32 v71, 0, v69, v71
	v_add3_u32 v69, v71, v70, v73
	ds_write_b128 v69, v[120:123] offset:32768
	v_add_u32_e32 v69, 16, v67
	v_and_b32_e32 v70, 0xfffff0, v69
	v_lshlrev_b32_e32 v74, 1, v69
	v_and_or_b32 v70, v74, 8, v70
	v_lshrrev_b32_e32 v70, 1, v70
	v_or_b32_e32 v70, v70, v72
	v_lshlrev_b32_e32 v70, 9, v70
	v_add3_u32 v70, v71, v70, v73
	ds_write_b128 v70, v[124:127] offset:32768
	v_ashrrev_i32_e32 v70, 4, v66
	v_and_b32_e32 v71, 15, v66
	v_lshlrev_b32_e32 v72, 9, v70
	v_lshlrev_b32_e32 v73, 5, v71
	v_add3_u32 v76, s50, v72, v73
	v_add_u32_e32 v72, 0, v73
	v_add_u32_e32 v84, 0x14000, v72
	ds_read_b128 v[72:75], v76
	ds_read_b128 v[76:79], v76 offset:16
	ds_read_b128 v[80:83], v84
	ds_read_b128 v[140:143], v84 offset:16
	v_lshlrev_b32_e32 v84, 16, v112
	s_waitcnt lgkmcnt(0)
	v_mul_f32_e32 v72, 0x3fb8aa3b, v72
	v_exp_f32_e32 v72, v72
	v_mul_f32_e32 v73, 0x3fb8aa3b, v73
	v_mul_f32_e32 v74, 0x3fb8aa3b, v74
	v_mul_f32_e32 v75, 0x3fb8aa3b, v75
	v_mul_f32_e32 v76, 0x3fb8aa3b, v76
	v_mul_f32_e32 v77, 0x3fb8aa3b, v77
	v_exp_f32_e32 v73, v73
	v_exp_f32_e32 v74, v74
	v_exp_f32_e32 v75, v75
	v_exp_f32_e32 v76, v76
	v_exp_f32_e32 v77, v77
	v_mul_f32_e32 v78, 0x3fb8aa3b, v78
	v_mul_f32_e32 v79, 0x3fb8aa3b, v79
	v_exp_f32_e32 v78, v78
	v_exp_f32_e32 v79, v79
	v_lshlrev_b32_e32 v145, 16, v113
	v_and_b32_e32 v146, 0xffff0000, v113
	v_lshlrev_b32_e32 v147, 16, v114
	v_and_b32_e32 v148, 0xffff0000, v114
	v_rcp_f32_e32 v86, v72
	v_mul_f32_e32 v72, v72, v84
	v_mul_f32_e32 v84, 0x3fb8aa3b, v140
	v_rcp_f32_e32 v87, v73
	v_mul_f32_e32 v73, v73, v144
	v_rcp_f32_e32 v144, v74
	v_mul_f32_e32 v74, v74, v145
	v_rcp_f32_e32 v145, v75
	v_mul_f32_e32 v75, v75, v146
	v_rcp_f32_e32 v146, v76
	v_mul_f32_e32 v76, v76, v147
	v_exp_f32_e32 v140, v84
	v_rcp_f32_e32 v147, v77
	v_mul_f32_e32 v77, v77, v148
	v_mul_f32_e32 v84, 0x3fb8aa3b, v141
	v_lshlrev_b32_e32 v149, 16, v115
	v_and_b32_e32 v150, 0xffff0000, v115
	v_mul_f32_e32 v80, 0x3fb8aa3b, v80
	v_mul_f32_e32 v81, 0x3fb8aa3b, v81
	v_exp_f32_e32 v141, v84
	v_mul_f32_e32 v84, 0x3fb8aa3b, v142
	v_cvt_pk_bf16_f32 v72, v72, v73
	v_cvt_pk_bf16_f32 v73, v74, v75
	v_cvt_pk_bf16_f32 v74, v76, v77
	v_lshlrev_b32_e32 v76, 8, v70
	v_lshlrev_b32_e32 v71, 4, v71
	v_and_b32_e32 v77, 0x70, v66
	v_exp_f32_e32 v80, v80
	v_exp_f32_e32 v81, v81
	v_rcp_f32_e32 v148, v78
	v_mul_f32_e32 v78, v78, v149
	v_exp_f32_e32 v142, v84
	v_rcp_f32_e32 v149, v79
	v_mul_f32_e32 v79, v79, v150
	v_mul_f32_e32 v84, 0x3fb8aa3b, v143
	v_bitop3_b32 v76, v71, v76, v77 bitop3:0xde
	v_exp_f32_e32 v143, v84
	v_cvt_pk_bf16_f32 v75, v78, v79
	v_add_u32_e32 v84, 0, v76
	v_mul_f32_e32 v82, 0x3fb8aa3b, v82
	v_mul_f32_e32 v83, 0x3fb8aa3b, v83
	ds_write_b128 v84, v[72:75]
	v_lshlrev_b32_e32 v72, 16, v116
	v_and_b32_e32 v73, 0xffff0000, v116
	v_exp_f32_e32 v82, v82
	v_exp_f32_e32 v83, v83
	v_pk_mul_f32 v[72:73], v[86:87], v[72:73]
	v_and_b32_e32 v71, 48, v71
	v_pk_mul_f32 v[74:75], v[72:73], v[80:81]
	v_cvt_pk_bf16_f32 v72, v72, v73
	v_cvt_pk_bf16_f32 v76, v74, v75
	v_lshlrev_b32_e32 v74, 16, v117
	v_and_b32_e32 v75, 0xffff0000, v117
	v_pk_mul_f32 v[74:75], v[144:145], v[74:75]
	v_lshlrev_b32_e32 v80, 16, v119
	v_pk_mul_f32 v[78:79], v[74:75], v[82:83]
	v_cvt_pk_bf16_f32 v73, v74, v75
	v_lshlrev_b32_e32 v74, 16, v118
	v_and_b32_e32 v75, 0xffff0000, v118
	v_and_b32_e32 v81, 0xffff0000, v119
	v_pk_mul_f32 v[74:75], v[146:147], v[74:75]
	v_pk_mul_f32 v[80:81], v[148:149], v[80:81]
	v_cvt_pk_bf16_f32 v77, v78, v79
	v_pk_mul_f32 v[78:79], v[74:75], v[140:141]
	v_cvt_pk_bf16_f32 v74, v74, v75
	v_cvt_pk_bf16_f32 v75, v80, v81
	ds_write_b128 v84, v[72:75] offset:8192
	v_and_b32_e32 v72, 0xfffff0, v70
	v_lshlrev_b32_e32 v73, 1, v70
	v_and_or_b32 v72, v73, 8, v72
	v_lshrrev_b32_e32 v72, 1, v72
	v_bfe_u32 v74, v66, 2, 2
	v_lshrrev_b32_e32 v73, 1, v70
	v_or_b32_e32 v72, v72, v74
	v_and_b32_e32 v74, 3, v70
	v_and_or_b32 v73, v73, 4, v74
	v_pk_mul_f32 v[82:83], v[80:81], v[142:143]
	v_lshlrev_b32_e32 v73, 6, v73
	v_lshl_add_u32 v72, v72, 9, 0
	v_cvt_pk_bf16_f32 v78, v78, v79
	v_cvt_pk_bf16_f32 v79, v82, v83
	v_add3_u32 v71, v72, v73, v71
	s_andn2_b64 vcc, exec, s[36:37]
	ds_write_b128 v71, v[76:79] offset:16384
	s_cbranch_vccnz .LBB0_969
	s_add_i32 s14, s48, -3
	s_and_b64 s[0:1], s[12:13], exec
	s_cselect_b32 s0, s20, s14
	s_lshl_b32 s0, s0, 5
	v_sub_u32_e32 v71, 31, v70
	v_cndmask_b32_e64 v70, v71, v70, s[12:13]
	s_add_i32 s0, s0, s47
	v_and_b32_e32 v72, 0x78, v68
	v_add_u32_e32 v73, s0, v70
	v_mov_b64_e32 v[70:71], s[30:31]
	v_mad_i64_i32 v[70:71], s[14:15], v73, s39, v[70:71]
	v_lshlrev_b32_e32 v84, 1, v72
	v_lshl_add_u64 v[70:71], v[70:71], 0, v[84:85]
	flat_load_dwordx4 v[112:115], v[70:71] nt
	flat_load_dwordx4 v[116:119], v[70:71] offset:1024 nt
	v_sub_u32_e32 v70, 31, v67
	v_cndmask_b32_e64 v70, v70, v67, s[12:13]
	v_sub_u32_e32 v67, 15, v67
	v_add_u32_e32 v72, s0, v70
	v_mov_b64_e32 v[70:71], s[34:35]
	v_and_b32_e32 v68, 0xf8, v68
	v_cndmask_b32_e64 v67, v67, v69, s[12:13]
	v_mad_i64_i32 v[72:73], s[14:15], v72, s39, v[70:71]
	v_lshlrev_b32_e32 v84, 1, v68
	v_add_u32_e32 v67, s0, v67
	v_lshl_add_u64 v[72:73], v[72:73], 0, v[84:85]
	v_mad_i64_i32 v[68:69], s[14:15], v67, s39, v[70:71]
	v_lshl_add_u64 v[68:69], v[68:69], 0, v[84:85]
	flat_load_dwordx4 v[120:123], v[72:73] offset:2048 nt
	flat_load_dwordx4 v[124:127], v[68:69] offset:2048 nt
	s_and_b64 vcc, exec, s[8:9]
	s_cbranch_vccnz .LBB0_969
	v_and_b32_e32 v67, 31, v66
	v_bitop3_b32 v68, v66, 31, v66 bitop3:0xc
	v_cndmask_b32_e64 v67, v68, v67, s[12:13]
	v_or_b32_e32 v67, s0, v67
	v_lshlrev_b32_e32 v84, 7, v67
	v_lshl_add_u64 v[68:69], s[26:27], 0, v[84:85]
	v_and_b32_e32 v84, 32, v66
	v_lshl_add_u64 v[66:67], v[68:69], 0, v[84:85]
	flat_load_dwordx4 v[132:135], v[66:67] nt
	flat_load_dwordx4 v[136:139], v[66:67] offset:16 nt
	s_branch .LBB0_969
